# P0 rows loop: XN/PB stores nt as well (plus x loads nt in P0/P3)
# speedup vs baseline: 1.0283x; 1.0173x over previous
.LBB0_38:
	s_add_i32 s28, s56, s58
	s_cmpk_lt_i32 s28, 0x4000
	s_cselect_b32 s16, s28, s56
	s_ashr_i32 s57, s56, 31
	s_lshl_b64 s[46:47], s[56:57], 12
	v_lshl_add_u64 v[34:35], v[2:3], 0, s[46:47]
	global_load_dwordx4 v[18:21], v[4:5], off
	s_ashr_i32 s17, s16, 31
	global_load_dwordx4 v[22:25], v[34:35], off nt
	global_load_dwordx4 v[26:29], v[34:35], off offset:1024 nt
	global_load_dwordx4 v[30:33], v[34:35], off offset:3072 nt
	s_nop 0
	global_load_dwordx4 v[34:37], v[34:35], off offset:2048 nt
	s_lshl_b64 s[0:1], s[56:57], 10
	s_lshl_b64 s[50:51], s[16:17], 12
	s_lshl_b64 s[46:47], s[16:17], 10
	v_lshl_add_u64 v[38:39], v[6:7], 0, s[0:1]
	v_lshl_add_u64 v[64:65], v[2:3], 0, s[50:51]
	global_load_dwordx4 v[38:41], v[38:39], off nt
	v_lshl_add_u64 v[66:67], v[6:7], 0, s[46:47]
	global_load_dwordx4 v[42:45], v[64:65], off nt
	global_load_dwordx4 v[46:49], v[64:65], off offset:1024 nt
	global_load_dwordx4 v[50:53], v[64:65], off offset:3072 nt
	global_load_dwordx4 v[54:57], v[64:65], off offset:2048 nt
	global_load_dwordx4 v[58:61], v[66:67], off nt
	s_lshl_b64 s[0:1], s[16:17], 11
	v_lshl_add_u64 v[68:69], v[8:9], 0, s[0:1]
	s_lshl_b64 s[48:49], s[56:57], 11
	v_lshl_add_u64 v[62:63], v[8:9], 0, s[48:49]
	s_waitcnt vmcnt(9)
	v_pk_mul_f32 v[64:65], v[24:25], v[24:25]
	v_pk_mul_f32 v[66:67], v[22:23], v[22:23]
	s_waitcnt vmcnt(8)
	v_pk_mul_f32 v[70:71], v[28:29], v[28:29]
	v_pk_mul_f32 v[72:73], v[26:27], v[26:27]
	s_waitcnt vmcnt(6)
	v_mul_f32_e32 v74, v35, v35
	v_mul_f32_e32 v76, v37, v37
	v_pk_mov_b32 v[78:79], v[66:67], v[64:65] op_sel:[1,0]
	v_mov_b32_e32 v67, v65
	s_waitcnt vmcnt(4)
	v_pk_mul_f32 v[64:65], v[44:45], v[44:45]
	v_pk_mul_f32 v[80:81], v[42:43], v[42:43]
	v_pk_mov_b32 v[82:83], v[72:73], v[70:71] op_sel:[1,0]
	v_mov_b32_e32 v73, v71
	s_waitcnt vmcnt(3)
	v_pk_mul_f32 v[70:71], v[48:49], v[48:49]
	v_pk_mul_f32 v[84:85], v[46:47], v[46:47]
	v_mul_f32_e32 v89, v32, v32
	v_mul_f32_e32 v90, v33, v33
	v_pk_fma_f32 v[74:75], v[34:35], v[34:35], v[74:75] op_sel_hi:[1,1,0]
	v_pk_fma_f32 v[76:77], v[36:37], v[36:37], v[76:77] op_sel_hi:[1,1,0]
	v_pk_add_f32 v[66:67], v[78:79], v[66:67]
	v_pk_mov_b32 v[78:79], v[80:81], v[64:65] op_sel:[1,0]
	v_mov_b32_e32 v81, v65
	v_pk_add_f32 v[64:65], v[82:83], v[72:73]
	v_pk_mov_b32 v[72:73], v[84:85], v[70:71] op_sel:[1,0]
	v_mov_b32_e32 v85, v71
	v_mul_f32_e32 v87, v31, v31
	s_waitcnt vmcnt(1)
	v_mul_f32_e32 v86, v55, v55
	v_mul_f32_e32 v88, v57, v57
	v_mov_b32_e32 v75, v89
	v_mov_b32_e32 v77, v90
	v_pk_add_f32 v[78:79], v[78:79], v[80:81]
	v_pk_add_f32 v[72:73], v[72:73], v[84:85]
	v_mul_f32_e32 v17, v30, v30
	v_mul_f32_e32 v91, v50, v50
	v_mul_f32_e32 v92, v51, v51
	v_mul_f32_e32 v93, v52, v52
	v_mul_f32_e32 v94, v53, v53
	v_pk_fma_f32 v[70:71], v[54:55], v[54:55], v[86:87] op_sel_hi:[1,1,0]
	v_pk_fma_f32 v[82:83], v[56:57], v[56:57], v[88:89] op_sel_hi:[1,1,0]
	v_pk_add_f32 v[66:67], v[66:67], v[66:67] op_sel:[0,1] op_sel_hi:[1,0]
	v_pk_add_f32 v[64:65], v[64:65], v[64:65] op_sel:[0,1] op_sel_hi:[1,0]
	v_pk_add_f32 v[74:75], v[74:75], v[76:77]
	v_pk_add_f32 v[76:77], v[78:79], v[78:79] op_sel:[0,1] op_sel_hi:[1,0]
	v_pk_add_f32 v[72:73], v[72:73], v[72:73] op_sel:[0,1] op_sel_hi:[1,0]
	v_mov_b32_e32 v71, v93
	v_mov_b32_e32 v83, v94
	v_mov_b32_e32 v67, v17
	v_mov_b32_e32 v65, v87
	v_mov_b32_e32 v77, v91
	v_mov_b32_e32 v73, v92
	v_pk_add_f32 v[70:71], v[70:71], v[82:83]
	v_pk_add_f32 v[64:65], v[66:67], v[64:65]
	v_pk_add_f32 v[66:67], v[76:77], v[72:73]
	v_pk_add_f32 v[64:65], v[64:65], v[74:75]
	v_pk_add_f32 v[66:67], v[66:67], v[70:71]
	v_mov_b32_e32 v71, v64
	v_mov_b32_e32 v70, v66
	v_mov_b32_e32 v64, v67
	v_pk_add_f32 v[64:65], v[70:71], v[64:65]
	ds_bpermute_b32 v67, v11, v65
	ds_bpermute_b32 v66, v11, v64
	s_waitcnt lgkmcnt(0)
	v_pk_add_f32 v[64:65], v[64:65], v[66:67]
	ds_bpermute_b32 v67, v12, v65
	ds_bpermute_b32 v66, v12, v64
	s_waitcnt lgkmcnt(0)
	v_pk_add_f32 v[64:65], v[64:65], v[66:67]
	ds_bpermute_b32 v67, v13, v65
	ds_bpermute_b32 v66, v13, v64
	s_waitcnt lgkmcnt(0)
	v_pk_add_f32 v[64:65], v[64:65], v[66:67]
	ds_bpermute_b32 v67, v14, v65
	ds_bpermute_b32 v66, v14, v64
	s_waitcnt lgkmcnt(0)
	v_pk_add_f32 v[64:65], v[64:65], v[66:67]
	ds_bpermute_b32 v67, v15, v65
	ds_bpermute_b32 v66, v15, v64
	s_waitcnt lgkmcnt(0)
	v_pk_add_f32 v[64:65], v[64:65], v[66:67]
	ds_bpermute_b32 v67, v16, v65
	ds_bpermute_b32 v66, v16, v64
	s_waitcnt lgkmcnt(0)
	v_pk_add_f32 v[64:65], v[64:65], v[66:67]
	s_nop 0
	v_pk_fma_f32 v[64:65], v[64:65], s[14:15], v[10:11] op_sel_hi:[1,0,0]
	s_nop 0
	v_mul_f32_e32 v17, 0x4b800000, v65
	v_cmp_gt_f32_e64 s[0:1], s15, v65
	v_mul_f32_e32 v66, 0x4b800000, v64
	v_cmp_gt_f32_e32 vcc, s15, v64
	v_cndmask_b32_e64 v17, v65, v17, s[0:1]
	v_rsq_f32_e32 v17, v17
	v_cndmask_b32_e32 v64, v64, v66, vcc
	v_rsq_f32_e32 v65, v64
	v_mul_f32_e32 v64, 0x45800000, v17
	v_cndmask_b32_e64 v64, v17, v64, s[0:1]
	v_mul_f32_e32 v66, 0x45800000, v65
	v_cndmask_b32_e32 v66, v65, v66, vcc
	v_pk_mul_f32 v[22:23], v[64:65], v[22:23] op_sel_hi:[0,1]
	v_pk_mul_f32 v[24:25], v[64:65], v[24:25] op_sel_hi:[0,1]
	v_pk_mul_f32 v[42:43], v[66:67], v[42:43] op_sel_hi:[0,1]
	v_pk_mul_f32 v[44:45], v[66:67], v[44:45] op_sel_hi:[0,1]
	v_pk_mul_f32 v[24:25], v[24:25], v[20:21]
	v_pk_mul_f32 v[22:23], v[22:23], v[18:19]
	v_pk_mul_f32 v[20:21], v[44:45], v[20:21]
	v_pk_mul_f32 v[18:19], v[42:43], v[18:19]
	v_cvt_pk_bf16_f32 v22, v22, v23
	v_cvt_pk_bf16_f32 v23, v24, v25
	v_cvt_pk_bf16_f32 v18, v18, v19
	v_cvt_pk_bf16_f32 v19, v20, v21
	global_store_dwordx2 v[62:63], v[22:23], off nt
	global_store_dwordx2 v[68:69], v[18:19], off nt
	global_load_dwordx4 v[18:21], v[4:5], off offset:1024
	v_pk_mul_f32 v[22:23], v[64:65], v[26:27] op_sel_hi:[0,1]
	v_pk_mul_f32 v[24:25], v[64:65], v[28:29] op_sel_hi:[0,1]
	v_pk_mul_f32 v[26:27], v[66:67], v[46:47] op_sel_hi:[0,1]
	v_pk_mul_f32 v[28:29], v[66:67], v[48:49] op_sel_hi:[0,1]
	s_lshl_b64 s[0:1], s[56:57], 9
	v_pk_mul_f32 v[30:31], v[64:65], v[30:31] op_sel_hi:[0,1]
	v_pk_mul_f32 v[32:33], v[64:65], v[32:33] op_sel_hi:[0,1]
	s_add_i32 s56, s28, s58
	s_waitcnt vmcnt(0)
	v_pk_mul_f32 v[24:25], v[24:25], v[20:21]
	v_pk_mul_f32 v[22:23], v[22:23], v[18:19]
	v_pk_mul_f32 v[20:21], v[28:29], v[20:21]
	v_pk_mul_f32 v[18:19], v[26:27], v[18:19]
	v_cvt_pk_bf16_f32 v22, v22, v23
	v_cvt_pk_bf16_f32 v23, v24, v25
	v_cvt_pk_bf16_f32 v18, v18, v19
	v_cvt_pk_bf16_f32 v19, v20, v21
	global_store_dwordx2 v[62:63], v[22:23], off offset:512 nt
	global_store_dwordx2 v[68:69], v[18:19], off offset:512 nt
	global_load_dwordx4 v[18:21], v[4:5], off offset:2048
	v_pk_mul_f32 v[22:23], v[64:65], v[34:35] op_sel_hi:[0,1]
	v_pk_mul_f32 v[24:25], v[64:65], v[36:37] op_sel_hi:[0,1]
	v_pk_mul_f32 v[26:27], v[66:67], v[54:55] op_sel_hi:[0,1]
	v_pk_mul_f32 v[28:29], v[66:67], v[56:57] op_sel_hi:[0,1]
	v_pk_mul_f32 v[34:35], v[66:67], v[50:51] op_sel_hi:[0,1]
	v_pk_mul_f32 v[36:37], v[66:67], v[52:53] op_sel_hi:[0,1]
	s_waitcnt vmcnt(0)
	v_pk_mul_f32 v[24:25], v[24:25], v[20:21]
	v_pk_mul_f32 v[22:23], v[22:23], v[18:19]
	v_pk_mul_f32 v[20:21], v[28:29], v[20:21]
	v_pk_mul_f32 v[18:19], v[26:27], v[18:19]
	v_cvt_pk_bf16_f32 v22, v22, v23
	v_cvt_pk_bf16_f32 v23, v24, v25
	v_cvt_pk_bf16_f32 v18, v18, v19
	v_cvt_pk_bf16_f32 v19, v20, v21
	global_store_dwordx2 v[62:63], v[22:23], off offset:1024 nt
	global_store_dwordx2 v[68:69], v[18:19], off offset:1024 nt
	global_load_dwordx4 v[18:21], v[4:5], off offset:3072
	v_lshl_add_u64 v[22:23], v[0:1], 0, s[0:1]
	s_lshl_b64 s[0:1], s[16:17], 9
	s_cmpk_gt_i32 s56, 0x3fff
	v_lshl_add_u64 v[24:25], v[0:1], 0, s[0:1]
	v_cvt_pk_bf16_f32 v26, v38, v39
	v_cvt_pk_bf16_f32 v27, v40, v41
	v_cvt_pk_bf16_f32 v28, v58, v59
	v_cvt_pk_bf16_f32 v29, v60, v61
	s_waitcnt vmcnt(0)
	v_pk_mul_f32 v[32:33], v[32:33], v[20:21]
	v_pk_mul_f32 v[30:31], v[30:31], v[18:19]
	v_pk_mul_f32 v[20:21], v[36:37], v[20:21]
	v_pk_mul_f32 v[18:19], v[34:35], v[18:19]
	v_cvt_pk_bf16_f32 v30, v30, v31
	v_cvt_pk_bf16_f32 v31, v32, v33
	v_cvt_pk_bf16_f32 v18, v18, v19
	v_cvt_pk_bf16_f32 v19, v20, v21
	global_store_dwordx2 v[62:63], v[30:31], off offset:1536 nt
	global_store_dwordx2 v[68:69], v[18:19], off offset:1536 nt
	global_store_dwordx2 v[22:23], v[26:27], off nt
	global_store_dwordx2 v[24:25], v[28:29], off nt
	s_cbranch_scc0 .LBB0_38
